# v11 with the tail-convert slots equalised further: B1 13824->11648 (slot0 6016 / slot1 6016), B4 36352->33536 (slot3 7424 / slot4 7424)
# speedup vs baseline: 1.0089x; 1.0073x over previous
; #define LAS __attribute__((address_space(3)))
; __device__ __forceinline__ TrItem p0_item_of(const Params& p, int it, int lane) {
;     const float* W; bf16* WT; int K, N, map, r = it, f8 = 0;
;     ...
;     if (r < TR_FI) TR_FFN_IN(0)
;     else if ((r -= TR_FI) < TR_FO) TR_FFN_OUT(0)
;     else if ((r -= TR_FO) < TR_IN) { W = p.in[IN_EWI]; WT = (bf16*)(p.ws + WS_WEI); K = D; N = D_EIN; map = 2; }
;     else if ((r -= TR_IN) < TR_OUT) { W = p.in[IN_EWO]; WT = (bf16*)(p.ws + WS_WEO); K = D; N = D; map = 0; }
;     else if ((r -= TR_OUT) < TR_FI) TR_FFN_IN(1)
;     else if ((r -= TR_FI) < TR_FO) TR_FFN_OUT(1)
;     else if ((r -= TR_FO) < TR_FI) TR_FFN_IN(2)
;     else if ((r -= TR_FI) < TR_FO) TR_FFN_OUT(2)
;     else if ((r -= TR_FO) < TR_IN) { W = p.in[IN_OWI]; WT = (bf16*)(p.ws + WS_WOI); K = D; N = D_OIN; map = 3; }
;     else if ((r -= TR_IN) < TR_OUT) { W = p.in[IN_OWO]; WT = (bf16*)(p.ws + WS_WOO); K = D; N = D; map = 0; }
;     else if ((r -= TR_OUT) < TR_FI) TR_FFN_IN(3)
;     else { r -= TR_FI; TR_FFN_OUT(3) }
; __device__ __forceinline__ void tail_convert(const Params& p, LAS unsigned char* lds, int slot, int units, int lane, int wave) {
;     const int G = gridDim.x, c = blockIdx.x, rem = units % G;
;     if (rem != 0 && c < rem) return;
;     const int nw = rem ? G - rem : G, j = rem ? c - rem : c;
;     tr_range(p, lds, TR_SLOT[slot] + j * 8 + wave, nw * 8, TR_SLOT[slot + 1], lane, wave);
.LBB0_226:
	s_abs_i32 s0, s97
	v_cvt_f32_u32_e32 v2, s0
	s_sub_i32 s1, 0, s0
	v_rcp_iflag_f32_e32 v2, v2
	s_nop 0
	v_mul_f32_e32 v2, 0x4f7ffffe, v2
	v_cvt_u32_f32_e32 v2, v2
	s_nop 0
	v_readfirstlane_b32 s2, v2
	s_mul_i32 s1, s1, s2
	s_mul_hi_u32 s1, s2, s1
	s_add_i32 s2, s2, s1
	s_mul_hi_u32 s1, s2, 0xc60
	s_mul_i32 s1, s1, s0
	s_sub_i32 s1, 0xc60, s1
	s_sub_i32 s2, s1, s0
	s_cmp_ge_u32 s1, s0
	s_cselect_b32 s1, s2, s1
	s_sub_i32 s2, s1, s0
	s_cmp_ge_u32 s1, s0
	s_cselect_b32 s12, s2, s1
	s_cmp_lg_u32 s12, 0
	s_cselect_b64 s[0:1], -1, 0
	s_cmp_lt_i32 s86, s12
	s_cselect_b64 s[2:3], -1, 0
	s_and_b64 s[0:1], s[0:1], s[2:3]
	s_and_b64 vcc, exec, s[0:1]
	s_cbranch_vccnz .LBB0_300
	s_sub_i32 s0, s86, s12
	s_lshl_b32 s13, s0, 3
	v_readlane_b32 s0, v253, 31
	s_add_i32 s13, s13, s0
	s_add_i32 s18, s13, 0x1600
	s_cmpk_gt_i32 s18, 0x2d7f
	s_cbranch_scc1 .LBB0_300
	s_mov_b32 s1, 1
	s_cmp_gt_u32 s13, 0x7fffe9ff
	s_mov_b32 s21, 0
	s_cbranch_scc1 .LBB0_233
	s_cmpk_lt_u32 s18, 0x2100
	s_cbranch_scc1 .LBB0_234
	s_cmpk_gt_u32 s18, 0x2aff
	s_cbranch_scc0 .LBB0_235
	s_cmpk_gt_u32 s18, 0x2eff
	s_cbranch_scc0 .LBB0_236
	v_readlane_b32 s36, v253, 10
	v_readlane_b32 s48, v253, 22
	v_readlane_b32 s49, v253, 23
	v_readlane_b32 s50, v253, 24
	v_readlane_b32 s51, v253, 25
	s_mov_b64 s[28:29], s[48:49]
	s_add_i32 s14, s13, 0xffffe700
	s_mov_b64 s[30:31], s[50:51]
	s_add_u32 s2, s30, 0x5800000
	v_readlane_b32 s37, v253, 11
	v_readlane_b32 s38, v253, 12
	v_readlane_b32 s39, v253, 13
	v_readlane_b32 s40, v253, 14
	v_readlane_b32 s41, v253, 15
	v_readlane_b32 s42, v253, 16
	v_readlane_b32 s43, v253, 17
	v_readlane_b32 s44, v253, 18
	v_readlane_b32 s45, v253, 19
	v_readlane_b32 s46, v253, 20
	v_readlane_b32 s47, v253, 21
	s_addc_u32 s3, s31, 0
	s_mov_b64 s[0:1], 0
	s_branch .LBB0_237

; __device__ __forceinline__ TrItem p0_item_of(const Params& p, int it, int lane) {
;     const float* W; bf16* WT; int K, N, map, r = it, f8 = 0;
;     ...
;     if (r < TR_FI) TR_FFN_IN(0)
;     else if ((r -= TR_FI) < TR_FO) TR_FFN_OUT(0)
;     else if ((r -= TR_FO) < TR_IN) { W = p.in[IN_EWI]; WT = (bf16*)(p.ws + WS_WEI); K = D; N = D_EIN; map = 2; }
;     else if ((r -= TR_IN) < TR_OUT) { W = p.in[IN_EWO]; WT = (bf16*)(p.ws + WS_WEO); K = D; N = D; map = 0; }
;     else if ((r -= TR_OUT) < TR_FI) TR_FFN_IN(1)
;     else if ((r -= TR_FI) < TR_FO) TR_FFN_OUT(1)
;     else if ((r -= TR_FO) < TR_FI) TR_FFN_IN(2)
;     else if ((r -= TR_FI) < TR_FO) TR_FFN_OUT(2)
;     else if ((r -= TR_FO) < TR_IN) { W = p.in[IN_OWI]; WT = (bf16*)(p.ws + WS_WOI); K = D; N = D_OIN; map = 3; }
;     else if ((r -= TR_IN) < TR_OUT) { W = p.in[IN_OWO]; WT = (bf16*)(p.ws + WS_WOO); K = D; N = D; map = 0; }
;     else if ((r -= TR_OUT) < TR_FI) TR_FFN_IN(3)
;     else { r -= TR_FI; TR_FFN_OUT(3) }
; __device__ __forceinline__ void tr_range(const Params& p, LAS unsigned char* lds, int first, int stride, int end, int lane, int wave) {
;     ...
;     for (int it = first; it < end; it += stride) {
; #pragma unroll
;         for (int i = 0; i < 64; ++i) scr[i * 65 + lane] = ra[i];
;         const bool more = it + stride < end;
;         TrItem nxt = cur;
;         if (more) { nxt = p0_item_of(p, it + stride, lane);
; #pragma unroll
;             for (int i = 0; i < 64; ++i) ra[i] = nxt.src[(size_t)i * nxt.N]; }
.LBB0_265:
	s_waitcnt lgkmcnt(0)
	s_add_i32 s23, s23, s20
	s_add_i32 s0, s24, s23
	s_cmpk_lt_i32 s0, 0x2d80
	s_mov_b32 s21, s16
	s_mov_b32 s19, s17
	s_mov_b64 s[2:3], s[8:9]
	s_cbranch_scc0 .LBB0_300
.LBB0_266:
	v_add_u32_e32 v85, 0x400, v3
	s_waitcnt vmcnt(0)
	ds_write2_b32 v3, v15, v31 offset1:65
	ds_write2_b32 v3, v30, v27 offset0:130 offset1:195
	ds_write2_b32 v85, v25, v23 offset0:4 offset1:69
	ds_write2_b32 v85, v21, v19 offset0:134 offset1:199
	v_add_u32_e32 v85, 0x800, v3
	ds_write2_b32 v85, v74, v73 offset0:8 offset1:73
	ds_write2_b32 v85, v72, v71 offset0:138 offset1:203
	v_add_u32_e32 v85, 0xc00, v3
	ds_write2_b32 v85, v70, v69 offset0:12 offset1:77
	ds_write2_b32 v85, v68, v67 offset0:142 offset1:207
	v_add_u32_e32 v85, 0x1000, v3
	ds_write2_b32 v85, v79, v66 offset0:16 offset1:81
	ds_write2_b32 v85, v65, v64 offset0:146 offset1:211
	v_add_u32_e32 v85, 0x1400, v3
	ds_write2_b32 v85, v63, v62 offset0:20 offset1:85
	ds_write2_b32 v85, v61, v60 offset0:150 offset1:215
	v_add_u32_e32 v85, 0x1800, v3
	ds_write2_b32 v85, v78, v59 offset0:24 offset1:89
	ds_write2_b32 v85, v58, v57 offset0:154 offset1:219
	v_add_u32_e32 v85, 0x1c00, v3
	ds_write2_b32 v85, v56, v55 offset0:28 offset1:93
	ds_write2_b32 v85, v54, v53 offset0:158 offset1:223
	v_add_u32_e32 v85, 0x2000, v3
	ds_write2_b32 v85, v77, v52 offset0:32 offset1:97
	ds_write2_b32 v85, v51, v50 offset0:162 offset1:227
	v_add_u32_e32 v85, 0x2400, v3
	ds_write2_b32 v85, v49, v48 offset0:36 offset1:101
	ds_write2_b32 v85, v47, v46 offset0:166 offset1:231
	v_add_u32_e32 v85, 0x2800, v3
	ds_write2_b32 v85, v76, v45 offset0:40 offset1:105
	ds_write2_b32 v85, v44, v43 offset0:170 offset1:235
	v_add_u32_e32 v85, 0x2c00, v3
	ds_write2_b32 v85, v42, v41 offset0:44 offset1:109
	ds_write2_b32 v85, v40, v39 offset0:174 offset1:239
	v_add_u32_e32 v85, 0x3000, v3
	ds_write2_b32 v85, v75, v38 offset0:48 offset1:113
	ds_write2_b32 v85, v37, v36 offset0:178 offset1:243
	v_add_u32_e32 v85, 0x3400, v3
	s_add_i32 s0, s22, s23
	ds_write2_b32 v85, v35, v34 offset0:52 offset1:117
	ds_write2_b32 v85, v33, v32 offset0:182 offset1:247
	v_add_u32_e32 v85, 0x3800, v3
	s_add_i32 s18, s18, s20
	s_add_i32 s28, s0, 0x1600
	ds_write2_b32 v85, v28, v17 offset0:56 offset1:121
	ds_write2_b32 v85, v84, v83 offset0:186 offset1:251
	v_add_u32_e32 v85, 0x3c00, v3
	s_cmpk_gt_i32 s28, 0x2d7f
	ds_write2_b32 v85, v82, v81 offset0:60 offset1:125
	ds_write2_b32 v85, v80, v29 offset0:190 offset1:255
	s_cbranch_scc1 .LBB0_295
	s_cmpk_lt_i32 s28, 0x1600
	s_cbranch_scc1 .LBB0_273
	v_readlane_b32 s36, v253, 32
	v_readlane_b32 s37, v253, 33
	s_cmpk_gt_u32 s28, 0x20ff
	s_mov_b64 s[8:9], -1
	s_mov_b64 s[12:13], s[36:37]
	s_mov_b64 s[16:17], -1
	v_readlane_b32 s38, v253, 34
	v_readlane_b32 s39, v253, 35
	v_readlane_b32 s40, v253, 36
	v_readlane_b32 s41, v253, 37
	v_readlane_b32 s42, v253, 38
	v_readlane_b32 s43, v253, 39
	v_readlane_b32 s44, v253, 40
	v_readlane_b32 s45, v253, 41
	v_readlane_b32 s46, v253, 42
	v_readlane_b32 s47, v253, 43
	v_readlane_b32 s48, v253, 44
	v_readlane_b32 s49, v253, 45
	v_readlane_b32 s50, v253, 46
	v_readlane_b32 s51, v253, 47
	s_cbranch_scc0 .LBB0_277
	s_cmpk_gt_u32 s28, 0x2aff
	s_cbranch_scc0 .LBB0_274
	s_cmpk_gt_u32 s28, 0x2eff
	s_cbranch_scc0 .LBB0_298
	s_add_i32 s27, s0, 0xffffe700
	s_mov_b64 s[12:13], s[6:7]
	s_mov_b64 s[16:17], 0
	s_mov_b32 s26, 1
	s_cbranch_execz .LBB0_299
	s_mov_b64 s[10:11], 0x3000000
	s_movk_i32 s0, 0x2c00
	s_mov_b64 s[14:15], 0
	s_andn2_b64 vcc, exec, s[16:17]
	s_cbranch_vccz .LBB0_275
	s_branch .LBB0_276

; #define LAS __attribute__((address_space(3)))
; __device__ __forceinline__ void tail_convert(const Params& p, LAS unsigned char* lds, int slot, int units, int lane, int wave) {
;     const int G = gridDim.x, c = blockIdx.x, rem = units % G;
;     if (rem != 0 && c < rem) return;
;     const int nw = rem ? G - rem : G, j = rem ? c - rem : c;
;     tr_range(p, lds, TR_SLOT[slot] + j * 8 + wave, nw * 8, TR_SLOT[slot + 1], lane, wave);
.LBB0_548:
	s_abs_i32 s0, s97
	v_cvt_f32_u32_e32 v2, s0
	s_sub_i32 s1, 0, s0
	v_rcp_iflag_f32_e32 v2, v2
	s_nop 0
	v_mul_f32_e32 v2, 0x4f7ffffe, v2
	v_cvt_u32_f32_e32 v2, v2
	s_nop 0
	v_readfirstlane_b32 s2, v2
	s_mul_i32 s1, s1, s2
	s_mul_hi_u32 s1, s2, s1
	s_add_i32 s2, s2, s1
	s_mul_hi_u32 s1, s2, 0x5a0
	s_mul_i32 s1, s1, s0
	s_sub_i32 s1, 0x5a0, s1
	s_sub_i32 s2, s1, s0
	s_cmp_ge_u32 s1, s0
	s_cselect_b32 s1, s2, s1
	s_sub_i32 s2, s1, s0
	s_cmp_ge_u32 s1, s0
	s_cselect_b32 s14, s2, s1
	s_cmp_lg_u32 s14, 0
	s_cselect_b64 s[0:1], -1, 0
	s_cmp_lt_i32 s86, s14
	s_cselect_b64 s[2:3], -1, 0
	s_and_b64 s[0:1], s[0:1], s[2:3]
	s_and_b64 vcc, exec, s[0:1]
	s_cbranch_vccnz .LBB0_624
	s_sub_i32 s0, s86, s14
	s_addk_i32 s0, 0xfd70
	s_lshl_b32 s16, s0, 3
	v_readlane_b32 s0, v253, 31
	s_add_i32 s16, s16, s0
	s_add_i32 s18, s16, 0x4200
	s_cmpk_gt_i32 s18, 0x44ff
	s_cbranch_scc1 .LBB0_624
	s_mov_b32 s1, 1
	s_cmpk_lt_i32 s18, 0x1600
	s_mov_b32 s21, 0
	s_cbranch_scc1 .LBB0_555
	s_cmpk_gt_u32 s18, 0x20ff
	s_mov_b64 s[2:3], -1
	s_cbranch_scc0 .LBB0_556
	s_cmpk_gt_u32 s18, 0x2aff
	s_cbranch_scc0 .LBB0_558
	s_cmpk_gt_u32 s18, 0x2eff
	s_cbranch_scc0 .LBB0_559
	v_readlane_b32 s36, v253, 10
	v_readlane_b32 s48, v253, 22
	v_readlane_b32 s49, v253, 23
	v_readlane_b32 s50, v253, 24
	v_readlane_b32 s51, v253, 25
	s_mov_b64 s[20:21], s[48:49]
	s_add_i32 s15, s16, 0x1300
	s_mov_b64 s[22:23], s[50:51]
	s_add_u32 s6, s22, 0x5800000
	v_readlane_b32 s37, v253, 11
	v_readlane_b32 s38, v253, 12
	v_readlane_b32 s39, v253, 13
	v_readlane_b32 s40, v253, 14
	v_readlane_b32 s41, v253, 15
	v_readlane_b32 s42, v253, 16
	v_readlane_b32 s43, v253, 17
	v_readlane_b32 s44, v253, 18
	v_readlane_b32 s45, v253, 19
	v_readlane_b32 s46, v253, 20
	v_readlane_b32 s47, v253, 21
	s_addc_u32 s7, s23, 0
	s_mov_b64 s[0:1], 0
	s_branch .LBB0_560

; #define LAS __attribute__((address_space(3)))
; __device__ __forceinline__ TrItem p0_item_of(const Params& p, int it, int lane) {
;     ...
;     const int nblk = N / 64, kb = r / nblk, nb = r % nblk, k0 = 64 * kb, n0 = 64 * nb;
;     TrItem t; t.src = W + (size_t)k0 * N + srccol(map, n0 + lane); t.N = N; t.K = K; t.fp8 = f8;
;     t.dst = f8 ? (bf16*)((unsigned char*)WT + (size_t)n0 * K + k0) : WT + (size_t)n0 * K + k0; return t;
; }
; __device__ __forceinline__ void tr_range(const Params& p, LAS unsigned char* lds, int first, int stride, int end, int lane, int wave) {
;     LAS float* scr = (LAS float*)(lds + wave * (64 * 65 * 4));
;     if (first >= end) return;
;     float ra[64];
;     TrItem cur = p0_item_of(p, first, lane);
; #pragma unroll
;     for (int i = 0; i < 64; ++i) ra[i] = cur.src[(size_t)i * cur.N];
.LBB0_587:
	s_add_u32 s15, s88, s8
	s_addc_u32 s9, s89, s9
	s_lshl_b32 s10, s13, 6
	s_ashr_i32 s11, s10, 31
	v_readlane_b32 s23, v253, 31
	s_mul_i32 s13, s11, s0
	s_mul_hi_u32 s16, s10, s0
	s_sub_i32 s1, s97, s14
	s_mul_i32 s8, s23, 0x4100
	s_add_i32 s17, s16, s13
	s_mul_i32 s16, s10, s0
	s_lshl_b32 s20, s1, 3
	s_add_i32 s8, s8, 0
	s_lshl_b64 s[16:17], s[16:17], 2
	s_add_u32 s6, s6, s16
	s_addc_u32 s7, s7, s17
	v_ashrrev_i32_e32 v3, 31, v2
	v_lshl_add_u64 v[2:3], v[2:3], 2, s[6:7]
	s_mul_hi_i32 s7, s12, s19
	s_mul_i32 s6, s12, s19
	s_lshl_b64 s[12:13], s[6:7], 1
	s_add_u32 s16, s15, s12
	s_addc_u32 s17, s9, s13
	s_lshl_b64 s[12:13], s[10:11], 1
	s_add_u32 s12, s16, s12
	s_addc_u32 s13, s17, s13
	s_add_u32 s6, s15, s6
	s_addc_u32 s7, s9, s7
	s_add_u32 s6, s6, s10
	s_addc_u32 s7, s7, s11
	s_mov_b32 s1, 0
	s_and_b64 s[2:3], s[2:3], exec
	s_cselect_b32 s3, s13, s7
	s_cselect_b32 s2, s12, s6
	s_mul_i32 s6, s0, 63
	s_mov_b32 s7, s1
	v_lshl_add_u64 v[4:5], s[6:7], 2, v[2:3]
	s_mul_i32 s6, s0, 62
	v_lshl_add_u64 v[6:7], s[6:7], 2, v[2:3]
	s_mul_i32 s6, s0, 61
	v_lshl_add_u64 v[8:9], s[6:7], 2, v[2:3]
	s_mul_i32 s6, s0, 60
	v_lshl_add_u64 v[10:11], s[6:7], 2, v[2:3]
	s_mul_i32 s6, s0, 59
	v_lshl_add_u64 v[12:13], s[6:7], 2, v[2:3]
	s_mul_i32 s6, s0, 58
	v_lshl_add_u64 v[14:15], s[6:7], 2, v[2:3]
	s_mul_i32 s6, s0, 57
	v_lshl_add_u64 v[16:17], s[6:7], 2, v[2:3]
	s_mul_i32 s6, s0, 56
	v_lshl_add_u64 v[18:19], s[6:7], 2, v[2:3]
	s_mul_i32 s6, s0, 55
	v_lshl_add_u64 v[20:21], s[6:7], 2, v[2:3]
	s_mul_i32 s6, s0, 54
	v_lshl_add_u64 v[22:23], s[6:7], 2, v[2:3]
	s_mul_i32 s6, s0, 53
	v_lshl_add_u64 v[24:25], s[6:7], 2, v[2:3]
	s_mul_i32 s6, s0, 52
	v_lshl_add_u64 v[26:27], s[6:7], 2, v[2:3]
	s_mul_i32 s6, s0, 51
	v_lshl_add_u64 v[30:31], s[6:7], 2, v[2:3]
	s_mul_i32 s6, s0, 50
	v_lshl_add_u64 v[38:39], s[6:7], 2, v[2:3]
	s_mul_i32 s6, s0, 49
	v_lshl_add_u64 v[40:41], s[6:7], 2, v[2:3]
	s_mul_i32 s6, s0, 48
	global_load_dword v28, v[18:19], off
	global_load_dword v32, v[20:21], off
	global_load_dword v33, v[22:23], off
	global_load_dword v34, v[24:25], off
	global_load_dword v35, v[26:27], off
	global_load_dword v36, v[30:31], off
	global_load_dword v37, v[38:39], off
	s_nop 0
	global_load_dword v38, v[40:41], off
	v_lshl_add_u64 v[18:19], s[6:7], 2, v[2:3]
	s_mul_i32 s6, s0, 47
	v_lshl_add_u64 v[20:21], s[6:7], 2, v[2:3]
	s_mul_i32 s6, s0, 46
	v_lshl_add_u64 v[22:23], s[6:7], 2, v[2:3]
	s_mul_i32 s6, s0, 45
	v_lshl_add_u64 v[24:25], s[6:7], 2, v[2:3]
	s_mul_i32 s6, s0, 44
	v_lshl_add_u64 v[26:27], s[6:7], 2, v[2:3]
	s_mul_i32 s6, s0, 43
	v_lshl_add_u64 v[30:31], s[6:7], 2, v[2:3]
	s_mul_i32 s6, s0, 42
	v_lshl_add_u64 v[44:45], s[6:7], 2, v[2:3]
	s_mul_i32 s6, s0, 41
	v_lshl_add_u64 v[46:47], s[6:7], 2, v[2:3]
	s_mul_i32 s6, s0, 40
	global_load_dword v75, v[18:19], off
	global_load_dword v39, v[20:21], off
	global_load_dword v40, v[22:23], off
	global_load_dword v41, v[24:25], off
	global_load_dword v42, v[26:27], off
	global_load_dword v43, v[30:31], off
	s_nop 0
	global_load_dword v44, v[44:45], off
	s_nop 0
	global_load_dword v45, v[46:47], off
	v_lshl_add_u64 v[18:19], s[6:7], 2, v[2:3]
	s_mul_i32 s6, s0, 39
	v_lshl_add_u64 v[20:21], s[6:7], 2, v[2:3]
	s_mul_i32 s6, s0, 38
	v_lshl_add_u64 v[22:23], s[6:7], 2, v[2:3]
	s_mul_i32 s6, s0, 37
	v_lshl_add_u64 v[24:25], s[6:7], 2, v[2:3]
	s_mul_i32 s6, s0, 36
	v_lshl_add_u64 v[26:27], s[6:7], 2, v[2:3]
	s_mul_i32 s6, s0, 35
	v_lshl_add_u64 v[30:31], s[6:7], 2, v[2:3]
	s_mul_i32 s6, s0, 34
	v_lshl_add_u64 v[52:53], s[6:7], 2, v[2:3]
	s_mul_i32 s6, s0, 33
	v_lshl_add_u64 v[54:55], s[6:7], 2, v[2:3]
	s_lshl_b32 s6, s0, 5
	global_load_dword v76, v[18:19], off
	global_load_dword v46, v[20:21], off
	global_load_dword v47, v[22:23], off
	global_load_dword v48, v[24:25], off
	global_load_dword v49, v[26:27], off
	global_load_dword v50, v[30:31], off
	global_load_dword v51, v[52:53], off
	s_nop 0
	global_load_dword v52, v[54:55], off
	v_lshl_add_u64 v[18:19], s[6:7], 2, v[2:3]
	s_mul_i32 s6, s0, 31
	v_lshl_add_u64 v[20:21], s[6:7], 2, v[2:3]
	s_mul_i32 s6, s0, 30
	v_lshl_add_u64 v[22:23], s[6:7], 2, v[2:3]
	s_mul_i32 s6, s0, 29
	v_lshl_add_u64 v[24:25], s[6:7], 2, v[2:3]
	s_mul_i32 s6, s0, 28
	v_lshl_add_u64 v[26:27], s[6:7], 2, v[2:3]
	s_mul_i32 s6, s0, 27
	v_lshl_add_u64 v[30:31], s[6:7], 2, v[2:3]
	s_mul_i32 s6, s0, 26
	v_lshl_add_u64 v[58:59], s[6:7], 2, v[2:3]
	s_mul_i32 s6, s0, 25
	v_lshl_add_u64 v[60:61], s[6:7], 2, v[2:3]
	s_mul_i32 s6, s0, 24
	global_load_dword v77, v[18:19], off
	global_load_dword v53, v[20:21], off
	global_load_dword v54, v[22:23], off
	global_load_dword v55, v[24:25], off
; #define LAS __attribute__((address_space(3)))
; __device__ __forceinline__ TrItem p0_item_of(const Params& p, int it, int lane) {
;     ...
;     const int nblk = N / 64, kb = r / nblk, nb = r % nblk, k0 = 64 * kb, n0 = 64 * nb;
;     TrItem t; t.src = W + (size_t)k0 * N + srccol(map, n0 + lane); t.N = N; t.K = K; t.fp8 = f8;
;     t.dst = f8 ? (bf16*)((unsigned char*)WT + (size_t)n0 * K + k0) : WT + (size_t)n0 * K + k0; return t;
; }
; __device__ __forceinline__ void tr_range(const Params& p, LAS unsigned char* lds, int first, int stride, int end, int lane, int wave) {
;     LAS float* scr = (LAS float*)(lds + wave * (64 * 65 * 4));
;     if (first >= end) return;
;     float ra[64];
;     TrItem cur = p0_item_of(p, first, lane);
; #pragma unroll
;     for (int i = 0; i < 64; ++i) ra[i] = cur.src[(size_t)i * cur.N];
; #pragma unroll 1
;     for (int it = first; it < end; it += stride) {
; #pragma unroll
;         for (int i = 0; i < 64; ++i) scr[i * 65 + lane] = ra[i];
;         const bool more = it + stride < end;
;         TrItem nxt = cur;
;         if (more) { nxt = p0_item_of(p, it + stride, lane);
; #pragma unroll
;             for (int i = 0; i < 64; ++i) ra[i] = nxt.src[(size_t)i * nxt.N]; }
	global_load_dword v56, v[26:27], off
	global_load_dword v57, v[30:31], off
	s_nop 0
	global_load_dword v58, v[58:59], off
	s_nop 0
	global_load_dword v59, v[60:61], off
	v_lshl_add_u64 v[18:19], s[6:7], 2, v[2:3]
	s_mul_i32 s6, s0, 23
	v_lshl_add_u64 v[20:21], s[6:7], 2, v[2:3]
	s_mul_i32 s6, s0, 22
	v_lshl_add_u64 v[22:23], s[6:7], 2, v[2:3]
	s_mul_i32 s6, s0, 21
	v_lshl_add_u64 v[24:25], s[6:7], 2, v[2:3]
	s_mul_i32 s6, s0, 20
	v_lshl_add_u64 v[26:27], s[6:7], 2, v[2:3]
	s_mul_i32 s6, s0, 19
	v_lshl_add_u64 v[30:31], s[6:7], 2, v[2:3]
	s_mul_i32 s6, s0, 18
	v_lshl_add_u64 v[66:67], s[6:7], 2, v[2:3]
	s_mul_i32 s6, s0, 17
	v_lshl_add_u64 v[68:69], s[6:7], 2, v[2:3]
	s_lshl_b32 s6, s0, 4
	global_load_dword v78, v[18:19], off
	global_load_dword v60, v[20:21], off
	global_load_dword v61, v[22:23], off
	global_load_dword v62, v[24:25], off
	global_load_dword v63, v[26:27], off
	global_load_dword v64, v[30:31], off
	global_load_dword v65, v[66:67], off
	s_nop 0
	global_load_dword v66, v[68:69], off
	v_lshl_add_u64 v[18:19], s[6:7], 2, v[2:3]
	s_mul_i32 s6, s0, 15
	v_lshl_add_u64 v[20:21], s[6:7], 2, v[2:3]
	s_mul_i32 s6, s0, 14
	v_lshl_add_u64 v[22:23], s[6:7], 2, v[2:3]
	s_mul_i32 s6, s0, 13
	v_lshl_add_u64 v[24:25], s[6:7], 2, v[2:3]
	s_mul_i32 s6, s0, 12
	v_lshl_add_u64 v[26:27], s[6:7], 2, v[2:3]
	s_mul_i32 s6, s0, 11
	v_lshl_add_u64 v[30:31], s[6:7], 2, v[2:3]
	s_mul_i32 s6, s0, 10
	v_lshl_add_u64 v[72:73], s[6:7], 2, v[2:3]
	s_mul_i32 s6, s0, 9
	v_lshl_add_u64 v[80:81], s[6:7], 2, v[2:3]
	s_lshl_b32 s6, s0, 3
	global_load_dword v79, v[18:19], off
	global_load_dword v67, v[20:21], off
	global_load_dword v68, v[22:23], off
	global_load_dword v69, v[24:25], off
	global_load_dword v70, v[26:27], off
	global_load_dword v71, v[30:31], off
	s_nop 0
	global_load_dword v72, v[72:73], off
	s_nop 0
	global_load_dword v73, v[80:81], off
	v_lshl_add_u64 v[18:19], s[6:7], 2, v[2:3]
	s_mul_i32 s6, s0, 7
	v_lshl_add_u64 v[20:21], s[6:7], 2, v[2:3]
	s_mul_i32 s6, s0, 6
	v_lshl_add_u64 v[22:23], s[6:7], 2, v[2:3]
	s_mul_i32 s6, s0, 5
	v_lshl_add_u64 v[24:25], s[6:7], 2, v[2:3]
	s_lshl_b32 s6, s0, 2
	v_lshl_add_u64 v[26:27], s[6:7], 2, v[2:3]
	s_mul_i32 s6, s0, 3
	v_lshl_add_u64 v[30:31], s[6:7], 2, v[2:3]
	s_lshl_b32 s6, s0, 1
	v_lshl_add_u64 v[80:81], s[6:7], 2, v[2:3]
	v_lshl_add_u64 v[82:83], s[0:1], 2, v[2:3]
	global_load_dword v74, v[18:19], off
	s_nop 0
	global_load_dword v19, v[20:21], off
	s_nop 0
	global_load_dword v21, v[22:23], off
	s_nop 0
	global_load_dword v23, v[24:25], off
	s_nop 0
	global_load_dword v25, v[26:27], off
	s_nop 0
	global_load_dword v27, v[30:31], off
	s_nop 0
	global_load_dword v30, v[80:81], off
	global_load_dword v31, v[82:83], off
	global_load_dword v29, v[4:5], off
	s_nop 0
	global_load_dword v80, v[6:7], off
	global_load_dword v81, v[8:9], off
	global_load_dword v82, v[10:11], off
	global_load_dword v83, v[12:13], off
	global_load_dword v84, v[14:15], off
	s_nop 0
	global_load_dword v17, v[16:17], off
	s_nop 0
	global_load_dword v15, v[2:3], off
	v_readlane_b32 s36, v253, 10
	v_readlane_b32 s48, v253, 22
	v_readlane_b32 s49, v253, 23
	v_lshlrev_b32_e32 v4, 3, v0
	v_readlane_b32 s50, v253, 24
	v_readlane_b32 s51, v253, 25
	s_mov_b64 s[24:25], s[48:49]
	v_lshrrev_b32_e32 v6, 3, v1
	v_and_b32_e32 v4, 56, v4
	s_mov_b64 s[26:27], s[50:51]
	v_mul_u32_u24_e32 v8, 0x104, v130
	v_mul_u32_u24_e32 v11, 0x104, v4
	v_and_b32_e32 v9, 60, v1
	v_lshlrev_b32_e32 v13, 2, v6
	s_add_u32 s6, s26, 0x5800000
	v_lshl_add_u32 v3, v1, 2, s8
	v_add3_u32 v9, s8, v8, v9
	v_add3_u32 v11, s8, v11, v13
	s_addc_u32 s7, s27, 0
	s_lshl_b32 s0, s97, 3
	s_lshl_b32 s8, s14, 4
	s_sub_i32 s22, s0, s8
	s_lshl_b32 s0, s86, 3
	s_addk_i32 s0, 0xeb80
	v_lshrrev_b32_e32 v2, 2, v1
	v_mov_b32_e32 v5, 0
	s_add_i32 s23, s23, s0
	s_lshl_b32 s0, s14, 3
	v_and_b32_e32 v7, 31, v0
	v_mov_b32_e32 v131, v5
	v_or_b32_e32 v8, 16, v2
	v_or_b32_e32 v10, 32, v2
	v_or_b32_e32 v12, 48, v2
	v_or_b32_e32 v14, 8, v6
	v_or_b32_e32 v16, 16, v6
	v_or_b32_e32 v18, 24, v6
	v_or_b32_e32 v20, 32, v6
	v_or_b32_e32 v22, 40, v6
	v_or_b32_e32 v24, 48, v6
	v_or_b32_e32 v26, 56, v6
	s_sub_i32 s24, 0x4200, s0
	s_mov_b32 s25, 0xc3e00000
	v_lshlrev_b32_e32 v4, 1, v4
	v_mov_b32_e32 v13, 0x43e00000
	s_mov_b32 s16, s21
	s_mov_b64 s[8:9], s[2:3]
	s_mov_b32 s17, s19
	v_readlane_b32 s37, v253, 11
	v_readlane_b32 s38, v253, 12
	v_readlane_b32 s39, v253, 13
	v_readlane_b32 s40, v253, 14
	v_readlane_b32 s41, v253, 15
	v_readlane_b32 s42, v253, 16
	v_readlane_b32 s43, v253, 17
	v_readlane_b32 s44, v253, 18
	v_readlane_b32 s45, v253, 19
	v_readlane_b32 s46, v253, 20
	v_readlane_b32 s47, v253, 21
	s_branch .LBB0_590

; #define LAS __attribute__((address_space(3)))
; __device__ __forceinline__ TrItem p0_item_of(const Params& p, int it, int lane) {
;     const float* W; bf16* WT; int K, N, map, r = it, f8 = 0;
;     ...
;     if (r < TR_FI) TR_FFN_IN(0)
;     else if ((r -= TR_FI) < TR_FO) TR_FFN_OUT(0)
;     else if ((r -= TR_FO) < TR_IN) { W = p.in[IN_EWI]; WT = (bf16*)(p.ws + WS_WEI); K = D; N = D_EIN; map = 2; }
;     else if ((r -= TR_IN) < TR_OUT) { W = p.in[IN_EWO]; WT = (bf16*)(p.ws + WS_WEO); K = D; N = D; map = 0; }
;     else if ((r -= TR_OUT) < TR_FI) TR_FFN_IN(1)
;     else if ((r -= TR_FI) < TR_FO) TR_FFN_OUT(1)
;     else if ((r -= TR_FO) < TR_FI) TR_FFN_IN(2)
;     else if ((r -= TR_FI) < TR_FO) TR_FFN_OUT(2)
;     else if ((r -= TR_FO) < TR_IN) { W = p.in[IN_OWI]; WT = (bf16*)(p.ws + WS_WOI); K = D; N = D_OIN; map = 3; }
;     else if ((r -= TR_IN) < TR_OUT) { W = p.in[IN_OWO]; WT = (bf16*)(p.ws + WS_WOO); K = D; N = D; map = 0; }
;     else if ((r -= TR_OUT) < TR_FI) TR_FFN_IN(3)
;     else { r -= TR_FI; TR_FFN_OUT(3) }
; __device__ __forceinline__ void tail_convert(const Params& p, LAS unsigned char* lds, int slot, int units, int lane, int wave) {
;     const int G = gridDim.x, c = blockIdx.x, rem = units % G;
;     if (rem != 0 && c < rem) return;
;     const int nw = rem ? G - rem : G, j = rem ? c - rem : c;
;     tr_range(p, lds, TR_SLOT[slot] + j * 8 + wave, nw * 8, TR_SLOT[slot + 1], lane, wave);
.LBB0_1455:
	s_abs_i32 s0, s97
	v_cvt_f32_u32_e32 v2, s0
	s_sub_i32 s1, 0, s0
	v_rcp_iflag_f32_e32 v2, v2
	s_nop 0
	v_mul_f32_e32 v2, 0x4f7ffffe, v2
	v_cvt_u32_f32_e32 v2, v2
	s_nop 0
	v_readfirstlane_b32 s2, v2
	s_mul_i32 s1, s1, s2
	s_mul_hi_u32 s1, s2, s1
	s_add_i32 s2, s2, s1
	s_mul_hi_u32 s1, s2, 0xc60
	s_mul_i32 s1, s1, s0
	s_sub_i32 s1, 0xc60, s1
	s_sub_i32 s2, s1, s0
	s_cmp_ge_u32 s1, s0
	s_cselect_b32 s1, s2, s1
	s_sub_i32 s2, s1, s0
	s_cmp_ge_u32 s1, s0
	s_cselect_b32 s46, s2, s1
	s_cmp_lg_u32 s46, 0
	s_cselect_b64 s[0:1], -1, 0
	s_cmp_lt_i32 s86, s46
	s_cselect_b64 s[2:3], -1, 0
	s_and_b64 s[0:1], s[0:1], s[2:3]
	s_and_b64 vcc, exec, s[0:1]
	s_cbranch_vccnz .LBB0_1602
	s_sub_i32 s0, s86, s46
	s_addk_i32 s0, 0xfea0
	s_lshl_b32 s18, s0, 3
	s_add_i32 s18, s18, s96
	s_add_i32 s33, s18, 0x7100
	s_cmp_gt_i32 s33, 0x82ff
	s_cbranch_scc1 .LBB0_1602
	s_cmpk_gt_i32 s33, 0x15ff
	v_writelane_b32 v252, s76, 24
	s_cbranch_scc0 .LBB0_1469
	s_cmpk_gt_u32 s33, 0x20ff
	s_cbranch_scc0 .LBB0_1470
	s_cmpk_gt_u32 s33, 0x2aff
	s_cbranch_scc0 .LBB0_1471
	s_cmpk_gt_u32 s33, 0x2eff
	s_cbranch_scc0 .LBB0_1472
	s_cmpk_gt_u32 s33, 0x44ff
	s_cbranch_scc0 .LBB0_1473
	s_cmpk_gt_u32 s33, 0x4fff
	s_cbranch_scc0 .LBB0_1474
	s_cmpk_gt_u32 s33, 0x65ff
	s_cbranch_scc0 .LBB0_1475
	s_cmp_lt_u32 s18, 0xffff8f00
	s_cbranch_scc0 .LBB0_1476
	s_cmpk_gt_u32 s33, 0x7aff
	s_cbranch_scc0 .LBB0_1477
	s_cmpk_gt_u32 s33, 0x7eff
	s_cbranch_scc0 .LBB0_1478
	s_cmpk_gt_u32 s33, 0x94ff
	s_mov_b64 s[10:11], -1
	s_cbranch_scc0 .LBB0_1479
	v_readlane_b32 s68, v253, 32
	v_readlane_b32 s69, v253, 33
	v_readlane_b32 s70, v253, 34
	v_readlane_b32 s71, v253, 35
	s_mov_b64 s[0:1], s[68:69]
	s_add_i32 s19, s18, 0xffffdc00
	s_mov_b64 s[2:3], s[70:71]
	s_add_u32 s2, s0, 0x8400000
	s_addc_u32 s3, s1, 0
	s_add_u32 s4, s88, 0xf600000
	v_readlane_b32 s72, v253, 36
	v_readlane_b32 s73, v253, 37
	v_readlane_b32 s74, v253, 38
	v_readlane_b32 s75, v253, 39
	v_readlane_b32 s76, v253, 40
	v_readlane_b32 s77, v253, 41
	v_readlane_b32 s78, v253, 42
	v_readlane_b32 s79, v253, 43
	v_readlane_b32 s80, v253, 44
	v_readlane_b32 s81, v253, 45
	v_readlane_b32 s82, v253, 46
	v_readlane_b32 s83, v253, 47
	s_addc_u32 s5, s89, 0
	s_mov_b64 s[0:1], 0
	s_branch .LBB0_1480

; __device__ __forceinline__ TrItem p0_item_of(const Params& p, int it, int lane) {
;     const float* W; bf16* WT; int K, N, map, r = it, f8 = 0;
;     ...
;     if (r < TR_FI) TR_FFN_IN(0)
;     else if ((r -= TR_FI) < TR_FO) TR_FFN_OUT(0)
;     else if ((r -= TR_FO) < TR_IN) { W = p.in[IN_EWI]; WT = (bf16*)(p.ws + WS_WEI); K = D; N = D_EIN; map = 2; }
;     else if ((r -= TR_IN) < TR_OUT) { W = p.in[IN_EWO]; WT = (bf16*)(p.ws + WS_WEO); K = D; N = D; map = 0; }
;     else if ((r -= TR_OUT) < TR_FI) TR_FFN_IN(1)
;     else if ((r -= TR_FI) < TR_FO) TR_FFN_OUT(1)
;     else if ((r -= TR_FO) < TR_FI) TR_FFN_IN(2)
;     else if ((r -= TR_FI) < TR_FO) TR_FFN_OUT(2)
;     else if ((r -= TR_FO) < TR_IN) { W = p.in[IN_OWI]; WT = (bf16*)(p.ws + WS_WOI); K = D; N = D_OIN; map = 3; }
;     else if ((r -= TR_IN) < TR_OUT) { W = p.in[IN_OWO]; WT = (bf16*)(p.ws + WS_WOO); K = D; N = D; map = 0; }
;     else if ((r -= TR_OUT) < TR_FI) TR_FFN_IN(3)
;     else { r -= TR_FI; TR_FFN_OUT(3) }
; __device__ __forceinline__ void tr_range(const Params& p, LAS unsigned char* lds, int first, int stride, int end, int lane, int wave) {
;     ...
;     for (int it = first; it < end; it += stride) {
; #pragma unroll
;         for (int i = 0; i < 64; ++i) scr[i * 65 + lane] = ra[i];
;         const bool more = it + stride < end;
;         TrItem nxt = cur;
;         if (more) { nxt = p0_item_of(p, it + stride, lane);
; #pragma unroll
;             for (int i = 0; i < 64; ++i) ra[i] = nxt.src[(size_t)i * nxt.N]; }
.LBB0_1534:
	s_waitcnt lgkmcnt(0)
	s_add_i32 s80, s80, s78
	s_add_i32 s0, s81, s80
	s_cmp_lt_i32 s0, 0x8300
	s_mov_b32 s75, s88
	s_mov_b32 s74, s83
	s_mov_b64 s[2:3], s[46:47]
	s_cbranch_scc0 .LBB0_1601
.LBB0_1535:
	v_add_u32_e32 v28, 0x400, v3
	s_waitcnt vmcnt(0)
	ds_write2_b32 v3, v85, v58 offset1:65
	ds_write2_b32 v3, v57, v56 offset0:130 offset1:195
	ds_write2_b32 v28, v55, v54 offset0:4 offset1:69
	ds_write2_b32 v28, v53, v84 offset0:134 offset1:199
	v_add_u32_e32 v28, 0x800, v3
	ds_write2_b32 v28, v71, v83 offset0:8 offset1:73
	ds_write2_b32 v28, v52, v51 offset0:138 offset1:203
	v_add_u32_e32 v28, 0xc00, v3
	ds_write2_b32 v28, v50, v49 offset0:12 offset1:77
	ds_write2_b32 v28, v48, v82 offset0:142 offset1:207
	v_add_u32_e32 v28, 0x1000, v3
	ds_write2_b32 v28, v70, v81 offset0:16 offset1:81
	ds_write2_b32 v28, v47, v46 offset0:146 offset1:211
	v_add_u32_e32 v28, 0x1400, v3
	ds_write2_b32 v28, v45, v44 offset0:20 offset1:85
	ds_write2_b32 v28, v43, v80 offset0:150 offset1:215
	v_add_u32_e32 v28, 0x1800, v3
	ds_write2_b32 v28, v69, v79 offset0:24 offset1:89
	ds_write2_b32 v28, v42, v41 offset0:154 offset1:219
	v_add_u32_e32 v28, 0x1c00, v3
	ds_write2_b32 v28, v40, v39 offset0:28 offset1:93
	ds_write2_b32 v28, v38, v78 offset0:158 offset1:223
	v_add_u32_e32 v28, 0x2000, v3
	ds_write2_b32 v28, v68, v77 offset0:32 offset1:97
	ds_write2_b32 v28, v37, v36 offset0:162 offset1:227
	v_add_u32_e32 v28, 0x2400, v3
	ds_write2_b32 v28, v35, v34 offset0:36 offset1:101
	ds_write2_b32 v28, v33, v76 offset0:166 offset1:231
	v_add_u32_e32 v28, 0x2800, v3
	ds_write2_b32 v28, v67, v75 offset0:40 offset1:105
	ds_write2_b32 v28, v32, v31 offset0:170 offset1:235
	v_add_u32_e32 v28, 0x2c00, v3
	ds_write2_b32 v28, v30, v27 offset0:44 offset1:109
	ds_write2_b32 v28, v25, v74 offset0:174 offset1:239
	v_add_u32_e32 v28, 0x3000, v3
	ds_write2_b32 v28, v66, v73 offset0:48 offset1:113
	ds_write2_b32 v28, v23, v21 offset0:178 offset1:243
	v_add_u32_e32 v28, 0x3400, v3
	s_add_i32 s0, s79, s80
	ds_write2_b32 v28, v19, v17 offset0:52 offset1:117
	ds_write2_b32 v28, v15, v72 offset0:182 offset1:247
	v_add_u32_e32 v28, 0x3800, v3
	s_add_i32 s33, s33, s78
	s_add_i32 s73, s0, 0x7100
	ds_write2_b32 v28, v65, v64 offset0:56 offset1:121
	ds_write2_b32 v28, v63, v62 offset0:186 offset1:251
	v_add_u32_e32 v28, 0x3c00, v3
	s_cmp_gt_i32 s73, 0x82ff
	ds_write2_b32 v28, v61, v60 offset0:60 offset1:125
	ds_write2_b32 v28, v59, v86 offset0:190 offset1:255
	s_cbranch_scc1 .LBB0_1598
	s_cmpk_lt_i32 s73, 0x1600
	s_cbranch_scc1 .LBB0_1550
	s_cmpk_gt_u32 s73, 0x20ff
	s_cbranch_scc0 .LBB0_1551
	s_cmpk_gt_u32 s73, 0x2aff
	s_cbranch_scc0 .LBB0_1552
	s_cmpk_gt_u32 s73, 0x2eff
	s_cbranch_scc0 .LBB0_1553
	s_cmpk_gt_u32 s73, 0x44ff
	s_mov_b64 s[70:71], -1
	s_cbranch_scc0 .LBB0_1572
	s_cmpk_gt_u32 s73, 0x4fff
	s_cbranch_scc0 .LBB0_1569
	s_cmpk_gt_u32 s73, 0x65ff
	s_cbranch_scc0 .LBB0_1566
	s_cmpk_gt_u32 s73, 0x70ff
	s_cbranch_scc0 .LBB0_1563
	s_cmpk_gt_u32 s73, 0x7aff
	s_cbranch_scc0 .LBB0_1554
	s_cmpk_gt_u32 s73, 0x7eff
	s_cbranch_scc0 .LBB0_1555
	s_mov_b64 s[68:69], -1
	s_cmpk_gt_u32 s73, 0x94ff
	s_mov_b64 s[46:47], -1
	s_cbranch_scc0 .LBB0_1548
	s_add_i32 s72, s0, 0xffffdc00
	s_mov_b64 s[46:47], 0

; #define LAS __attribute__((address_space(3)))
; __device__ __forceinline__ void tail_convert(const Params& p, LAS unsigned char* lds, int slot, int units, int lane, int wave) {
;     const int G = gridDim.x, c = blockIdx.x, rem = units % G;
;     if (rem != 0 && c < rem) return;
;     const int nw = rem ? G - rem : G, j = rem ? c - rem : c;
;     tr_range(p, lds, TR_SLOT[slot] + j * 8 + wave, nw * 8, TR_SLOT[slot + 1], lane, wave);
.LBB0_1929:
	s_abs_i32 s0, s97
	s_waitcnt vmcnt(0)
	v_cvt_f32_u32_e32 v2, s0
	s_sub_i32 s1, 0, s0
	v_rcp_iflag_f32_e32 v2, v2
	s_nop 0
	v_mul_f32_e32 v2, 0x4f7ffffe, v2
	v_cvt_u32_f32_e32 v2, v2
	s_nop 0
	v_readfirstlane_b32 s2, v2
	s_mul_i32 s1, s1, s2
	s_mul_hi_u32 s1, s2, s1
	s_add_i32 s2, s2, s1
	s_mul_hi_u32 s1, s2, 0x5a0
	s_mul_i32 s1, s1, s0
	s_sub_i32 s1, 0x5a0, s1
	s_sub_i32 s2, s1, s0
	s_cmp_ge_u32 s1, s0
	s_cselect_b32 s1, s2, s1
	s_sub_i32 s2, s1, s0
	s_cmp_ge_u32 s1, s0
	s_cselect_b32 s44, s2, s1
	s_cmp_lg_u32 s44, 0
	s_cselect_b64 s[0:1], -1, 0
	s_cmp_lt_i32 s86, s44
	s_cselect_b64 s[2:3], -1, 0
	s_and_b64 s[0:1], s[0:1], s[2:3]
	s_and_b64 vcc, exec, s[0:1]
	s_cbranch_vccnz .LBB0_2078
	s_sub_i32 s0, s86, s44
	s_addk_i32 s0, 0xfcc0
	s_lshl_b32 s16, s0, 3
	s_add_i32 s34, s16, s96
	s_add_i32 s33, s34, 0x9d00
	s_cmp_gt_i32 s33, 0x9fff
	s_cbranch_scc1 .LBB0_2078
	s_cmpk_gt_i32 s33, 0x15ff
	s_cbranch_scc0 .LBB0_1944
	s_cmpk_gt_u32 s33, 0x20ff
	s_cbranch_scc0 .LBB0_1945
	s_cmpk_gt_u32 s33, 0x2aff
	s_cbranch_scc0 .LBB0_1946
	s_cmpk_gt_u32 s33, 0x2eff
	s_cbranch_scc0 .LBB0_1947
	s_cmpk_gt_u32 s33, 0x44ff
	s_cbranch_scc0 .LBB0_1948
	s_cmpk_gt_u32 s33, 0x4fff
	s_cbranch_scc0 .LBB0_1949
	s_cmpk_gt_u32 s33, 0x65ff
	s_cbranch_scc0 .LBB0_1950
	s_cmpk_gt_u32 s33, 0x70ff
	s_cbranch_scc0 .LBB0_1951
	s_cmpk_gt_u32 s33, 0x7aff
	s_cbranch_scc0 .LBB0_1952
	s_cmpk_gt_u32 s33, 0x7eff
	s_cbranch_scc0 .LBB0_1953
	s_mov_b32 s12, s76
	s_cmpk_gt_u32 s33, 0x94ff
	s_mov_b64 s[8:9], -1
	s_cbranch_scc0 .LBB0_1954
	v_readlane_b32 s68, v253, 32
	v_readlane_b32 s69, v253, 33
	v_readlane_b32 s70, v253, 34
	v_readlane_b32 s71, v253, 35
	s_mov_b64 s[0:1], s[68:69]
	s_add_i32 s17, s34, 0x800
	s_mov_b64 s[2:3], s[70:71]
	s_add_u32 s2, s0, 0x8400000
	s_addc_u32 s3, s1, 0
	s_add_u32 s4, s88, 0xf600000
	v_readlane_b32 s72, v253, 36
	v_readlane_b32 s73, v253, 37
	v_readlane_b32 s74, v253, 38
	v_readlane_b32 s75, v253, 39
	v_readlane_b32 s76, v253, 40
	v_readlane_b32 s77, v253, 41
	v_readlane_b32 s78, v253, 42
	v_readlane_b32 s79, v253, 43
	v_readlane_b32 s80, v253, 44
	v_readlane_b32 s81, v253, 45
	v_readlane_b32 s82, v253, 46
	v_readlane_b32 s83, v253, 47
	s_addc_u32 s5, s89, 0
	s_mov_b64 s[0:1], 0
	s_branch .LBB0_1955

; __device__ __forceinline__ void tr_range(const Params& p, LAS unsigned char* lds, int first, int stride, int end, int lane, int wave) {
;     ...
;     TrItem cur = p0_item_of(p, first, lane);
; #pragma unroll
;     for (int i = 0; i < 64; ++i) ra[i] = cur.src[(size_t)i * cur.N];
.LBB0_2008:
	s_lshl_b32 s10, s19, 6
	s_ashr_i32 s11, s10, 31
	s_mul_i32 s9, s11, s0
	s_mul_hi_u32 s16, s10, s0
	s_sub_i32 s1, s97, s44
	s_mul_i32 s8, s96, 0x4100
	s_add_i32 s17, s16, s9
	s_mul_i32 s16, s10, s0
	s_lshl_b32 s70, s1, 3
	s_add_i32 s8, s8, 0
	s_lshl_b64 s[16:17], s[16:17], 2
	s_add_u32 s2, s2, s16
	s_addc_u32 s3, s3, s17
	v_ashrrev_i32_e32 v3, 31, v2
	v_lshl_add_u64 v[2:3], v[2:3], 2, s[2:3]
	s_ashr_i32 s2, s18, 31
	s_mul_hi_u32 s3, s18, s68
	s_mul_i32 s2, s2, s68
	s_add_i32 s3, s3, s2
	s_mul_i32 s2, s18, s68
	s_lshl_b64 s[16:17], s[2:3], 1
	s_add_u32 s9, s4, s16
	s_addc_u32 s18, s5, s17
	s_lshl_b64 s[16:17], s[10:11], 1
	s_add_u32 s9, s9, s16
	s_addc_u32 s16, s18, s17
	s_add_u32 s2, s4, s2
	s_addc_u32 s3, s5, s3
	s_add_u32 s4, s2, s10
	s_addc_u32 s5, s3, s11
	s_mov_b32 s1, 0
	s_and_b64 s[2:3], s[6:7], exec
	s_cselect_b32 s3, s16, s5
	s_cselect_b32 s2, s9, s4
	s_mul_i32 s4, s0, 63
	s_mov_b32 s5, s1
	v_lshl_add_u64 v[4:5], s[4:5], 2, v[2:3]
	s_mul_i32 s4, s0, 62
	global_load_dword v86, v[4:5], off
	v_lshl_add_u64 v[4:5], s[4:5], 2, v[2:3]
	s_mul_i32 s4, s0, 61
	global_load_dword v59, v[4:5], off
	v_lshl_add_u64 v[4:5], s[4:5], 2, v[2:3]
	s_mul_i32 s4, s0, 60
	global_load_dword v60, v[4:5], off
	v_lshl_add_u64 v[4:5], s[4:5], 2, v[2:3]
	s_mul_i32 s4, s0, 59
	global_load_dword v61, v[4:5], off
	v_lshl_add_u64 v[4:5], s[4:5], 2, v[2:3]
	s_mul_i32 s4, s0, 58
	global_load_dword v62, v[4:5], off
	v_lshl_add_u64 v[4:5], s[4:5], 2, v[2:3]
	s_mul_i32 s4, s0, 57
	global_load_dword v63, v[4:5], off
	v_lshl_add_u64 v[4:5], s[4:5], 2, v[2:3]
	s_mul_i32 s4, s0, 56
	global_load_dword v64, v[4:5], off
	v_lshl_add_u64 v[4:5], s[4:5], 2, v[2:3]
	s_mul_i32 s4, s0, 55
	global_load_dword v65, v[4:5], off
	v_lshl_add_u64 v[4:5], s[4:5], 2, v[2:3]
	s_mul_i32 s4, s0, 54
	global_load_dword v72, v[4:5], off
	v_lshl_add_u64 v[4:5], s[4:5], 2, v[2:3]
	s_mul_i32 s4, s0, 53
	global_load_dword v15, v[4:5], off
	v_lshl_add_u64 v[4:5], s[4:5], 2, v[2:3]
	s_mul_i32 s4, s0, 52
	global_load_dword v17, v[4:5], off
	v_lshl_add_u64 v[4:5], s[4:5], 2, v[2:3]
	s_mul_i32 s4, s0, 51
	global_load_dword v19, v[4:5], off
	v_lshl_add_u64 v[4:5], s[4:5], 2, v[2:3]
	s_mul_i32 s4, s0, 50
	global_load_dword v21, v[4:5], off
	v_lshl_add_u64 v[4:5], s[4:5], 2, v[2:3]
	s_mul_i32 s4, s0, 49
	global_load_dword v23, v[4:5], off
	v_lshl_add_u64 v[4:5], s[4:5], 2, v[2:3]
	s_mul_i32 s4, s0, 48
	global_load_dword v73, v[4:5], off
	v_lshl_add_u64 v[4:5], s[4:5], 2, v[2:3]
	s_mul_i32 s4, s0, 47
	global_load_dword v66, v[4:5], off
	v_lshl_add_u64 v[4:5], s[4:5], 2, v[2:3]
	s_mul_i32 s4, s0, 46
	global_load_dword v74, v[4:5], off
	v_lshl_add_u64 v[4:5], s[4:5], 2, v[2:3]
	s_mul_i32 s4, s0, 45
	global_load_dword v25, v[4:5], off
	v_lshl_add_u64 v[4:5], s[4:5], 2, v[2:3]
	s_mul_i32 s4, s0, 44
	global_load_dword v27, v[4:5], off
	v_lshl_add_u64 v[4:5], s[4:5], 2, v[2:3]
	s_mul_i32 s4, s0, 43
	global_load_dword v30, v[4:5], off
	v_lshl_add_u64 v[4:5], s[4:5], 2, v[2:3]
	s_mul_i32 s4, s0, 42
	global_load_dword v31, v[4:5], off
	v_lshl_add_u64 v[4:5], s[4:5], 2, v[2:3]
	s_mul_i32 s4, s0, 41
	global_load_dword v32, v[4:5], off
	v_lshl_add_u64 v[4:5], s[4:5], 2, v[2:3]
	s_mul_i32 s4, s0, 40
	global_load_dword v75, v[4:5], off
	v_lshl_add_u64 v[4:5], s[4:5], 2, v[2:3]
	s_mul_i32 s4, s0, 39
	global_load_dword v67, v[4:5], off
	v_lshl_add_u64 v[4:5], s[4:5], 2, v[2:3]
	s_mul_i32 s4, s0, 38
	global_load_dword v76, v[4:5], off
	v_lshl_add_u64 v[4:5], s[4:5], 2, v[2:3]
	s_mul_i32 s4, s0, 37
	global_load_dword v33, v[4:5], off
	v_lshl_add_u64 v[4:5], s[4:5], 2, v[2:3]
	s_mul_i32 s4, s0, 36
	global_load_dword v34, v[4:5], off
	v_lshl_add_u64 v[4:5], s[4:5], 2, v[2:3]
	s_mul_i32 s4, s0, 35
	global_load_dword v35, v[4:5], off
	v_lshl_add_u64 v[4:5], s[4:5], 2, v[2:3]
	s_mul_i32 s4, s0, 34
	global_load_dword v36, v[4:5], off
	v_lshl_add_u64 v[4:5], s[4:5], 2, v[2:3]
	s_mul_i32 s4, s0, 33
	global_load_dword v37, v[4:5], off
	v_lshl_add_u64 v[4:5], s[4:5], 2, v[2:3]
	s_lshl_b32 s4, s0, 5
	global_load_dword v77, v[4:5], off
	v_lshl_add_u64 v[4:5], s[4:5], 2, v[2:3]
	s_mul_i32 s4, s0, 31
	global_load_dword v68, v[4:5], off
	v_lshl_add_u64 v[4:5], s[4:5], 2, v[2:3]
	s_mul_i32 s4, s0, 30
	global_load_dword v78, v[4:5], off
	v_lshl_add_u64 v[4:5], s[4:5], 2, v[2:3]
	s_mul_i32 s4, s0, 29
	global_load_dword v38, v[4:5], off
	v_lshl_add_u64 v[4:5], s[4:5], 2, v[2:3]
	s_mul_i32 s4, s0, 28
	global_load_dword v39, v[4:5], off
	v_lshl_add_u64 v[4:5], s[4:5], 2, v[2:3]
	s_mul_i32 s4, s0, 27
	global_load_dword v40, v[4:5], off
	v_lshl_add_u64 v[4:5], s[4:5], 2, v[2:3]
	s_mul_i32 s4, s0, 26
	global_load_dword v41, v[4:5], off
	v_lshl_add_u64 v[4:5], s[4:5], 2, v[2:3]
	s_mul_i32 s4, s0, 25
	global_load_dword v42, v[4:5], off
	v_lshl_add_u64 v[4:5], s[4:5], 2, v[2:3]
	s_mul_i32 s4, s0, 24
	global_load_dword v79, v[4:5], off
	v_lshl_add_u64 v[4:5], s[4:5], 2, v[2:3]
	s_mul_i32 s4, s0, 23
	global_load_dword v69, v[4:5], off
	v_lshl_add_u64 v[4:5], s[4:5], 2, v[2:3]
	s_mul_i32 s4, s0, 22
	global_load_dword v80, v[4:5], off
	v_lshl_add_u64 v[4:5], s[4:5], 2, v[2:3]
	s_mul_i32 s4, s0, 21
	global_load_dword v43, v[4:5], off
	v_lshl_add_u64 v[4:5], s[4:5], 2, v[2:3]
	s_mul_i32 s4, s0, 20
	global_load_dword v44, v[4:5], off
	v_lshl_add_u64 v[4:5], s[4:5], 2, v[2:3]
	s_mul_i32 s4, s0, 19
; __device__ __forceinline__ void tr_range(const Params& p, LAS unsigned char* lds, int first, int stride, int end, int lane, int wave) {
;     ...
;     TrItem cur = p0_item_of(p, first, lane);
; #pragma unroll
;     for (int i = 0; i < 64; ++i) ra[i] = cur.src[(size_t)i * cur.N];
; #pragma unroll 1
;     for (int it = first; it < end; it += stride) {
; #pragma unroll
;         for (int i = 0; i < 64; ++i) scr[i * 65 + lane] = ra[i];
;         const bool more = it + stride < end;
;         TrItem nxt = cur;
;         if (more) { nxt = p0_item_of(p, it + stride, lane);
; #pragma unroll
;             for (int i = 0; i < 64; ++i) ra[i] = nxt.src[(size_t)i * nxt.N]; }
	global_load_dword v45, v[4:5], off
	v_lshl_add_u64 v[4:5], s[4:5], 2, v[2:3]
	s_mul_i32 s4, s0, 18
	global_load_dword v46, v[4:5], off
	v_lshl_add_u64 v[4:5], s[4:5], 2, v[2:3]
	s_mul_i32 s4, s0, 17
	global_load_dword v47, v[4:5], off
	v_lshl_add_u64 v[4:5], s[4:5], 2, v[2:3]
	s_lshl_b32 s4, s0, 4
	global_load_dword v81, v[4:5], off
	v_lshl_add_u64 v[4:5], s[4:5], 2, v[2:3]
	s_mul_i32 s4, s0, 15
	global_load_dword v70, v[4:5], off
	v_lshl_add_u64 v[4:5], s[4:5], 2, v[2:3]
	s_mul_i32 s4, s0, 14
	global_load_dword v82, v[4:5], off
	v_lshl_add_u64 v[4:5], s[4:5], 2, v[2:3]
	s_mul_i32 s4, s0, 13
	global_load_dword v48, v[4:5], off
	v_lshl_add_u64 v[4:5], s[4:5], 2, v[2:3]
	s_mul_i32 s4, s0, 12
	global_load_dword v49, v[4:5], off
	v_lshl_add_u64 v[4:5], s[4:5], 2, v[2:3]
	s_mul_i32 s4, s0, 11
	global_load_dword v50, v[4:5], off
	v_lshl_add_u64 v[4:5], s[4:5], 2, v[2:3]
	s_mul_i32 s4, s0, 10
	global_load_dword v51, v[4:5], off
	v_lshl_add_u64 v[4:5], s[4:5], 2, v[2:3]
	s_mul_i32 s4, s0, 9
	global_load_dword v52, v[4:5], off
	v_lshl_add_u64 v[4:5], s[4:5], 2, v[2:3]
	s_lshl_b32 s4, s0, 3
	global_load_dword v83, v[4:5], off
	v_lshl_add_u64 v[4:5], s[4:5], 2, v[2:3]
	s_mul_i32 s4, s0, 7
	global_load_dword v71, v[4:5], off
	v_lshl_add_u64 v[4:5], s[4:5], 2, v[2:3]
	s_mul_i32 s4, s0, 6
	global_load_dword v84, v[4:5], off
	v_lshl_add_u64 v[4:5], s[4:5], 2, v[2:3]
	s_mul_i32 s4, s0, 5
	global_load_dword v53, v[4:5], off
	v_lshl_add_u64 v[4:5], s[4:5], 2, v[2:3]
	s_lshl_b32 s4, s0, 2
	global_load_dword v54, v[4:5], off
	v_lshl_add_u64 v[4:5], s[4:5], 2, v[2:3]
	s_mul_i32 s4, s0, 3
	global_load_dword v55, v[4:5], off
	v_lshl_add_u64 v[4:5], s[4:5], 2, v[2:3]
	s_lshl_b32 s4, s0, 1
	global_load_dword v56, v[4:5], off
	v_lshl_add_u64 v[4:5], s[4:5], 2, v[2:3]
	global_load_dword v57, v[4:5], off
	v_lshl_add_u64 v[4:5], s[0:1], 2, v[2:3]
	global_load_dword v58, v[4:5], off
	global_load_dword v85, v[2:3], off
	v_readlane_b32 s16, v253, 32
	v_readlane_b32 s18, v253, 34
	v_readlane_b32 s19, v253, 35
	v_readlane_b32 s17, v253, 33
	s_mov_b64 s[38:39], s[18:19]
	s_mov_b64 s[36:37], s[16:17]
	s_add_u32 s4, s36, 0x8400000
	s_addc_u32 s5, s37, 0
	v_writelane_b32 v252, s4, 22
	v_readlane_b32 s20, v253, 36
	v_readlane_b32 s21, v253, 37
	v_readlane_b32 s22, v253, 38
	v_readlane_b32 s23, v253, 39
	v_readlane_b32 s24, v253, 40
	v_readlane_b32 s25, v253, 41
	v_readlane_b32 s26, v253, 42
	v_readlane_b32 s27, v253, 43
	v_readlane_b32 s28, v253, 44
	v_readlane_b32 s29, v253, 45
	v_readlane_b32 s30, v253, 46
	v_readlane_b32 s31, v253, 47
	v_writelane_b32 v252, s5, 23
	s_add_u32 s4, s88, 0xf600000
	s_addc_u32 s5, s89, 0
	v_readlane_b32 s16, v253, 10
	v_writelane_b32 v252, s4, 20
	v_readlane_b32 s30, v253, 24
	v_readlane_b32 s31, v253, 25
	v_writelane_b32 v252, s5, 21
	s_add_u32 s4, s30, 0x10800000
	s_addc_u32 s5, s31, 0
	v_writelane_b32 v252, s4, 18
	s_mov_b32 s14, s76
	v_lshlrev_b32_e32 v4, 3, v0
	v_writelane_b32 v252, s5, 19
	s_add_u32 s4, s88, 0x8800000
	s_addc_u32 s5, s89, 0
	s_add_u32 s76, s88, 0x13c00000
	s_addc_u32 s77, s89, 0
	s_add_u32 s12, s36, 0x5800000
	v_writelane_b32 v252, s4, 16
	s_addc_u32 s13, s37, 0
	v_lshrrev_b32_e32 v6, 3, v1
	v_writelane_b32 v252, s5, 17
	s_add_u32 s4, s88, 0xe000000
	s_addc_u32 s5, s89, 0
	v_and_b32_e32 v4, 56, v4
	s_add_u32 s6, s30, 0xb000000
	v_mul_u32_u24_e32 v8, 0x104, v146
	v_mul_u32_u24_e32 v11, 0x104, v4
	v_and_b32_e32 v9, 60, v1
	v_lshlrev_b32_e32 v13, 2, v6
	s_addc_u32 s7, s31, 0
	v_lshl_add_u32 v3, v1, 2, s8
	v_add3_u32 v9, s8, v8, v9
	v_add3_u32 v11, s8, v11, v13
	s_add_u32 s8, s88, 0x5c00000
	s_addc_u32 s9, s89, 0
	s_add_u32 s10, s36, 0x2c00000
	s_addc_u32 s11, s37, 0
	v_readlane_b32 s17, v253, 11
	s_add_u32 s16, s88, 0xca00000
	s_addc_u32 s17, s89, 0
	v_readlane_b32 s18, v253, 12
	v_readlane_b32 s19, v253, 13
	v_readlane_b32 s20, v253, 14
	v_readlane_b32 s21, v253, 15
	v_readlane_b32 s22, v253, 16
	v_readlane_b32 s23, v253, 17
	v_readlane_b32 s24, v253, 18
	v_readlane_b32 s25, v253, 19
	v_readlane_b32 s26, v253, 20
	v_readlane_b32 s27, v253, 21
	v_readlane_b32 s28, v253, 22
	v_readlane_b32 s29, v253, 23
	v_writelane_b32 v253, s16, 56
	v_lshrrev_b32_e32 v2, 2, v1
	v_mov_b32_e32 v5, 0
	v_writelane_b32 v253, s17, 57
	s_add_u32 s16, s30, 0x5800000
	s_addc_u32 s17, s31, 0
	s_add_u32 s34, s88, 0x3000000
	s_addc_u32 s35, s89, 0
	s_add_u32 s36, s88, 0x12000000
	s_addc_u32 s37, s89, 0
	s_add_u32 s38, s88, 0x10c00000
	s_addc_u32 s39, s89, 0
	s_add_u32 s40, s88, 0xb400000
	s_addc_u32 s41, s89, 0
	s_add_u32 s42, s88, 0x400000
	s_addc_u32 s43, s89, 0
	s_lshl_b32 s0, s97, 3
	s_lshl_b32 s45, s44, 4
	s_sub_i32 s71, s0, s45
	s_lshl_b32 s0, s86, 3
	s_addk_i32 s0, 0xe600
	v_writelane_b32 v253, s16, 54
	s_add_i32 s72, s96, s0
	s_lshl_b32 s0, s44, 3
	v_and_b32_e32 v7, 31, v0
	v_mov_b32_e32 v147, v5
	v_or_b32_e32 v8, 16, v2
	v_or_b32_e32 v10, 32, v2
	v_or_b32_e32 v12, 48, v2
	v_or_b32_e32 v14, 8, v6
	v_or_b32_e32 v16, 16, v6
	v_or_b32_e32 v18, 24, v6
	v_or_b32_e32 v20, 32, v6
	v_or_b32_e32 v22, 40, v6
	v_or_b32_e32 v24, 48, v6
	v_or_b32_e32 v26, 56, v6
	v_writelane_b32 v253, s17, 55
	s_sub_i32 s73, 0x9d00, s0
	s_mov_b32 s74, 0xc3e00000
	v_lshlrev_b32_e32 v4, 1, v4
	v_mov_b32_e32 v13, 0x43e00000
	s_mov_b32 s78, s69
	s_mov_b64 s[44:45], s[2:3]
	s_mov_b32 s75, s68
	s_branch .LBB0_2011
